# softmax scale (x log2e) folded into the bf16 queries of the differential and latent groups (one rounding, as before); 32 f32 multiplies per tile removed from their unmasked loops
# speedup vs baseline: 1.0059x; 1.0059x over previous
;     __host__ __device__ bool next(int i, Unit& u) const {
;         const long L = (long)i * G + c; if (L >= nwg) return false;
;         int wgid = (int)L; { const int q = nwg / NXCD, r = nwg % NXCD, xcd = wgid % NXCD, off = wgid / NXCD; wgid = (xcd < r ? xcd * (q + 1) : r * (q + 1) + (xcd - r) * q) + off; }
;         const int nig = WGM * nN, gid = wgid / nig, fm = gid * WGM, gsz = (nM - fm) < WGM ? (nM - fm) : WGM;
;         u.pm = fm + ((wgid % nig) % gsz); u.pn = (wgid % nig) / gsz; return true;
;     }
; __global__ void __launch_bounds__(512, 2) fwd_kernel(Args a_unused) {
;     ...
;         if (sp == 0 && (PHM & 2)) {
;             pg8::Gemm g{XB, (const bf16_t*)(ws + WS_WIN + l * SZ_WIN), SEQ, NINP, DM, DM}; pg8::StaticOrder S; S.init(SEQ, NINP, G, (int)blockIdx.x);
;             pg8::EpiScaleBf16<false> E{PROJ, NINP, SSQ + (2 * l) * SEQ};
;             pg8::gemm_phase<pg8::EpiScaleBf16<false>, pg8::StaticOrder, true, true>(lds, g, S, E);
;             if ((int)blockIdx.x >= (SEQ / 256) * (NINP / 256) - 2 * G) tr_drain(a, lds, tid_, (int*)(ws + WS_CNT) + 24 + 2 * l, l, 1, 1);
;         } else if (sp == 1 && (PHM & 4)) {
;             for (int m = gw; m < SEQ; m += NGW) post_proj_row(a, l, m, lane);
;         } else if (sp == 2 && (PHM & 8)) {
;             if ((int)blockIdx.x < 6) fox_cumsum(a, (int)blockIdx.x, lds);
;             { pg8::Gemm g{PROJ + C_MQ, (const bf16_t*)(ws + WS_WQUP + l * SZ_WQUP), SEQ, NQUPP, 512, NINP}; pg8::StaticOrder S; S.init(SEQ, NQUPP, G, (int)blockIdx.x);
;               pg8::EpiScaleBf16<false> E{QC, NQUPP, nullptr};
;               pg8::gemm_phase<pg8::EpiScaleBf16<false>, pg8::StaticOrder, true, true>(lds, g, S, E); }
;             { pg8::Gemm g{PROJ + C_CKV, (const bf16_t*)(ws + WS_WKVUP + l * SZ_WKVUP), SEQ, NKVUP, 256, NINP}; pg8::StaticOrder S; if (G == 256) S.init(SEQ, NKVUP, 96, (int)blockIdx.x >= 160 ? (int)blockIdx.x - 160 : 192); else S.init(SEQ, NKVUP, G, (int)((blockIdx.x + 128) % G));
;               pg8::EpiScaleBf16<false> E{KVC, NKVUP, nullptr};
;               pg8::gemm_phase<pg8::EpiScaleBf16<false>, pg8::StaticOrder, true, true>(lds, g, S, E); }
;         } else if (sp == 3 && (PHM & 16)) {
;             for (int m = gw; m < SEQ; m += NGW) post_mla_row(a, l, m, lane);
;         } else if (sp == 4 && (PHM & 32)) {
;             attention_phase<0>(a, l, lds, 0);
.LBB0_274:
	s_waitcnt lgkmcnt(0)
	s_lshr_b32 s0, s16, 16
	v_writelane_b32 v254, s0, 7
	s_and_b32 s0, s16, 0xffff
	s_lshl_b32 s2, s82, 3
	s_lshl_b32 s73, s22, 3
	s_cmpk_lt_i32 s82, 0x100
	s_cselect_b64 s[4:5], -1, 0
	s_ashr_i32 s84, s82, 31
	v_writelane_b32 v254, s2, 8
	s_lshr_b32 s2, s84, 29
	s_add_i32 s2, s82, s2
	s_ashr_i32 s6, s2, 3
	s_and_b32 s2, s2, -8
	s_sub_i32 s7, s82, s2
	s_mul_i32 s1, s23, s22
	s_lshl_b32 s2, s7, 5
	s_ashr_i32 s23, s22, 31
	v_writelane_b32 v254, s4, 9
	s_cmpk_lt_i32 s82, 0x400
	v_bfe_u32 v1, v0, 10, 10
	v_writelane_b32 v254, s5, 10
	s_cselect_b64 s[4:5], -1, 0
	v_writelane_b32 v254, s4, 11
	v_bfe_u32 v0, v0, 20, 10
	v_mad_u32_u24 v197, v0, s0, v1
	v_writelane_b32 v254, s5, 12
	s_lshl_b32 s4, s7, 7
	s_lshl_b32 s5, s0, 8
	s_cmp_lt_i32 s82, 6
	v_writelane_b32 v254, s5, 13
	s_cselect_b64 s[8:9], -1, 0
	v_writelane_b32 v254, s8, 14
	s_cmpk_lt_i32 s82, 0xa0
	s_mul_i32 s57, s1, s3
	v_writelane_b32 v254, s9, 15
	s_cselect_b64 s[8:9], -1, 0
	v_writelane_b32 v254, s8, 16
	s_cmpk_lg_i32 s22, 0x100
	v_cvt_f32_u32_e32 v0, s22
	v_writelane_b32 v254, s9, 17
	s_cselect_b64 s[8:9], -1, 0
	v_writelane_b32 v254, s8, 18
	s_add_i32 s5, s82, 0xffffff60
	v_rcp_iflag_f32_e32 v0, v0
	v_writelane_b32 v254, s9, 19
	s_add_i32 s8, s82, 0x80
	s_cmpk_gt_i32 s82, 0x9f
	s_cselect_b32 s5, s5, 0xc0
	s_cmpk_lt_i32 s82, 0x260
	v_writelane_b32 v254, s5, 20
	s_cselect_b64 s[10:11], -1, 0
	s_lshl_b32 s5, s22, 1
	s_sub_i32 s5, 0x260, s5
	v_writelane_b32 v254, s10, 21
	s_cmp_ge_i32 s82, s5
	s_mul_i32 s5, s7, 33
	v_writelane_b32 v254, s11, 22
	s_cselect_b64 s[10:11], -1, 0
	s_cmp_lt_i32 s7, 0
	s_mul_i32 s9, s7, 0x81
	s_cselect_b32 s0, s5, s2
	s_movk_i32 s2, 0x4d
	s_cselect_b32 s1, s9, s4
	s_cselect_b32 s3, 21, 20
	s_cselect_b32 s9, s2, 0x4c
	s_add_i32 s0, s0, s6
	s_ashr_i32 s2, s0, 31
	s_lshr_b32 s2, s2, 28
	s_add_i32 s2, s0, s2
	s_ashr_i32 s4, s2, 4
	s_and_b32 s2, s2, 0xfff0
	s_sub_i32 s2, s0, s2
	s_bfe_u32 s0, s2, 0x10007
	s_add_i32 s5, s2, s0
	s_bfe_i32 s0, s5, 0x80000
	s_and_b32 s5, s5, 0xfe
	v_writelane_b32 v254, s10, 23
	s_sub_i32 s2, s2, s5
	s_lshl_b32 s4, s4, 1
	v_writelane_b32 v254, s11, 24
	s_sext_i32_i16 s10, s0
	s_sext_i32_i8 s2, s2
	s_add_i32 s12, s4, s2
	s_ashr_i32 s2, s10, 1
	s_add_i32 s1, s1, s6
	v_writelane_b32 v254, s2, 25
	s_ashr_i32 s2, s1, 31
	s_lshr_b32 s2, s2, 25
	s_add_i32 s2, s1, s2
	s_ashr_i32 s4, s2, 7
	s_and_b32 s2, s2, 0xff80
	s_sub_i32 s1, s1, s2
	s_bfe_u32 s2, s1, 0x10007
	s_add_i32 s5, s1, s2
	s_bfe_i32 s2, s5, 0x80000
	s_and_b32 s5, s5, 0xfc
	s_sub_i32 s1, s1, s5
	s_lshr_b32 s0, s10, 1
	s_lshl_b32 s4, s4, 2
	s_sext_i32_i16 s10, s2
	s_sext_i32_i8 s1, s1
	s_mul_i32 s3, s7, s3
	s_add_i32 s14, s4, s1
	s_ashr_i32 s1, s10, 2
	s_add_i32 s3, s3, s6
	v_writelane_b32 v254, s1, 26
	s_mul_hi_i32 s1, s3, 0x66666667
	s_lshr_b32 s4, s1, 31
	s_ashr_i32 s1, s1, 2
	s_add_i32 s1, s1, s4
	s_mul_i32 s4, s1, 10
	s_sub_i32 s3, s3, s4
	s_bfe_u32 s4, s3, 0x10007
	s_add_i32 s5, s3, s4
	s_bfe_i32 s4, s5, 0x80000
	s_and_b32 s5, s5, 0xfe
	s_sub_i32 s3, s3, s5
	s_lshl_b32 s1, s1, 1
	s_sext_i32_i8 s3, s3
	s_lshr_b32 s2, s10, 2
	s_sext_i32_i16 s10, s4
	s_add_i32 s1, s1, s3
	s_lshr_b32 s4, s10, 1
	v_writelane_b32 v254, s1, 27
	s_ashr_i32 s1, s10, 1
	v_writelane_b32 v254, s1, 28
	s_bfe_i64 s[4:5], s[4:5], 0x100000
	s_mul_i32 s1, s7, s9
	s_lshl_b64 s[4:5], s[4:5], 18
	s_add_i32 s1, s1, s6
	v_writelane_b32 v254, s4, 29
	s_mul_hi_i32 s3, s1, 0x6bca1af3
	s_ashr_i32 s13, s12, 31
	v_writelane_b32 v254, s5, 30
	s_lshr_b32 s4, s3, 31
	s_ashr_i32 s3, s3, 4
	s_add_i32 s3, s3, s4
	s_lshl_b32 s5, s3, 1
	s_mul_i32 s3, s3, 38
	s_sub_i32 s1, s1, s3
	s_bfe_u32 s3, s1, 0x10007
	s_add_i32 s3, s1, s3
	s_bfe_i32 s4, s3, 0x80000
	s_and_b32 s3, s3, 0xfe
	s_sub_i32 s1, s1, s3
	s_sext_i32_i16 s6, s4
;     __host__ __device__ bool next(int i, Unit& u) const {
;         const long L = (long)i * G + c; if (L >= nwg) return false;
;         int wgid = (int)L; { const int q = nwg / NXCD, r = nwg % NXCD, xcd = wgid % NXCD, off = wgid / NXCD; wgid = (xcd < r ? xcd * (q + 1) : r * (q + 1) + (xcd - r) * q) + off; }
;         const int nig = WGM * nN, gid = wgid / nig, fm = gid * WGM, gsz = (nM - fm) < WGM ? (nM - fm) : WGM;
;         u.pm = fm + ((wgid % nig) % gsz); u.pn = (wgid % nig) / gsz; return true;
;     }
; template <int VARI>
; __device__ __forceinline__ void attention_phase(ArgsP a, int l, LAS unsigned char* lds, int cslot) {
;     ...
;             attn_unit<0, VARI>(lds, tu, p, 0.125f * LOG2E, lam, a->in[I_SUBLN] + l * 128, 1.0f - linit, 0.f, ub_a < 60.f);
;         } else if (id >= 256 && id < NU_B && (ATM & 2) && (VARI == 0 || (VARI & 2))) {
;             const int h = (id - 256) / QB_PER_HEAD, qb = (id - 256) % QB_PER_HEAD;
;             p.Q = PROJ + C_FQ + h * 128; p.qpitch = NINP; p.K0 = PROJ + C_FK + h * 128; p.k0pitch = NINP; p.K1 = p.K0; p.k1pitch = NINP;
;             p.V = PROJ + C_FV + h * 128; p.vpitch = NINP; p.cum = (const float*)(ws + WS_CUM) + h; p.O = MIX + 512 + h * 128; p.P0 = qb * UNIT_ROWS; p.rows = UNIT_ROWS;
;             attn_unit<1, VARI>(lds, tu, p, 0.08838834764831845f * LOG2E, 0.f, nullptr, 1.f, fox_u, fox_u < 60.f);
;         } else if (id >= NU_B && (ATM & 4) && (VARI == 0 || (VARI & 4))) {
;             const int h = (id - NU_B) / QB_PER_HEAD, qb = (id - NU_B) % QB_PER_HEAD;
;             p.Q = QC + h * 192; p.qpitch = NQUPP; p.K0 = PROJ + C_KR; p.k0pitch = NINP; p.K1 = KVC + h * 256; p.k1pitch = NKVUP;
;             p.V = KVC + h * 256 + 128; p.vpitch = NKVUP; p.cum = nullptr; p.O = MIX + 1280 + h * 128; p.P0 = qb * UNIT_ROWS; p.rows = UNIT_ROWS;
;             attn_unit<2, VARI>(lds, tu, p, 0.07216878364870322f * LOG2E, 0.f, nullptr, 1.f, 0.f, ub_c < 60.f);
	s_sext_i32_i8 s1, s1
	s_add_i32 s10, s5, s1
	s_ashr_i32 s1, s6, 1
	s_lshr_b32 s4, s6, 1
	v_writelane_b32 v254, s1, 31
	s_lshl_b64 s[6:7], s[12:13], 22
	v_writelane_b32 v254, s6, 32
	s_bfe_i64 s[0:1], s[0:1], 0x100000
	s_ashr_i32 s15, s14, 31
	v_writelane_b32 v254, s7, 33
	s_lshl_b64 s[6:7], s[0:1], 22
	v_writelane_b32 v254, s6, 34
	s_bfe_i64 s[2:3], s[2:3], 0x100000
	s_lshl_b64 s[2:3], s[2:3], 20
	v_writelane_b32 v254, s7, 35
	s_mov_b32 s6, s14
	v_writelane_b32 v254, s6, 36
	s_lshl_b64 s[0:1], s[0:1], 20
	s_ashr_i32 s11, s10, 31
	v_writelane_b32 v254, s7, 37
	s_lshl_b64 s[6:7], s[14:15], 20
	v_writelane_b32 v254, s6, 38
	v_mul_f32_e32 v0, 0x4f7ffffe, v0
	v_cvt_u32_f32_e32 v0, v0
	v_writelane_b32 v254, s7, 39
	v_writelane_b32 v254, s2, 40
	s_movk_i32 s89, 0xc00
	s_movk_i32 s81, 0x2600
	v_writelane_b32 v254, s3, 41
	s_mov_b32 s2, s12
	v_writelane_b32 v254, s2, 42
	s_mov_b32 s17, 0x10000
	v_mov_b32_e32 v1, 0
	v_writelane_b32 v254, s3, 43
	s_lshl_b64 s[2:3], s[12:13], 20
	v_writelane_b32 v254, s2, 44
	s_mov_b32 s24, 0x14000
	s_movk_i32 s86, 0x4000
	v_writelane_b32 v254, s3, 45
	v_writelane_b32 v254, s0, 46
	s_movk_i32 s3, 0xa00
	s_movk_i32 s93, 0x60
	v_writelane_b32 v254, s1, 47
	s_mov_b32 s0, s10
	v_writelane_b32 v254, s0, 48
	s_mov_b32 s87, 0x18000
	s_mov_b32 s74, 0x8000
	v_writelane_b32 v254, s1, 49
	s_lshl_b64 s[0:1], s[10:11], 20
	v_writelane_b32 v254, s0, 50
	s_mov_b32 s69, 0x1c000
	s_mov_b32 s78, 0xc000
	v_writelane_b32 v254, s1, 51
	s_bfe_i64 s[0:1], s[4:5], 0x100000
	s_lshl_b64 s[0:1], s[0:1], 20
	v_writelane_b32 v254, s0, 52
	v_mov_b32_e32 v198, 0x358637bd
	s_mov_b32 s16, 0x800000
	v_writelane_b32 v254, s1, 53
	s_sub_i32 s0, 0, s22
	v_readfirstlane_b32 s1, v0
	s_mul_i32 s0, s0, s1
	s_mul_hi_u32 s0, s1, s0
	s_add_i32 s1, s1, s0
	s_mul_hi_u32 s0, s8, s1
	s_mul_i32 s0, s0, s22
	s_sub_i32 s0, s8, s0
	s_sub_i32 s1, s0, s22
	s_cmp_ge_u32 s0, s22
	s_cselect_b32 s0, s1, s0
	s_sub_i32 s1, s0, s22
	s_cmp_ge_u32 s0, s22
	s_cselect_b32 s0, s1, s0
	v_writelane_b32 v254, s0, 54
	s_mul_i32 s0, s22, 0x6000
	s_mul_hi_i32 s1, s73, 0xc00
	v_writelane_b32 v254, s0, 55
	v_mov_b32_e32 v199, 0x2000
	v_mbcnt_lo_u32_b32 v0, -1, 0
	v_writelane_b32 v254, s1, 56
	s_mul_i32 s0, s22, 0x5000
	s_mul_hi_i32 s1, s73, 0xa00
	v_writelane_b32 v254, s0, 57
	v_mov_b32_e32 v216, 1
	v_mov_b64_e32 v[200:201], 0x100
	v_writelane_b32 v254, s1, 58
	s_lshl_b32 s0, s82, 8
	v_writelane_b32 v254, s0, 59
	s_lshl_b32 s0, s22, 8
	v_writelane_b32 v254, s0, 60
	s_mul_i32 s0, s22, 0x13000
	v_writelane_b32 v254, s0, 61
	s_lshl_b32 s0, s82, 6
	v_writelane_b32 v254, s0, 62
	s_lshl_b32 s0, s22, 6
	v_writelane_b32 v254, s0, 63
	s_mov_b32 s0, 0x20fc0
	s_add_i32 s88, s0, 0x100
	s_mov_b32 s0, 0x20080
	s_addk_i32 s0, 0x100
	v_writelane_b32 v255, s0, 0
	s_mov_b32 s0, 0x20084
	s_addk_i32 s0, 0x100
	v_writelane_b32 v255, s0, 1
	v_writelane_b32 v255, s73, 2
	v_writelane_b32 v255, s84, 3
	v_mov_b64_e32 v[202:203], 0xff
	v_mbcnt_hi_u32_b32 v217, -1, v0
	v_mov_b32_e32 v218, 0x7f800000
	v_mov_b32_e32 v219, 0xff800000
	v_mov_b32_e32 v220, 0x840
	v_mov_b32_e32 v221, 0x1080
	v_mov_b32_e32 v253, 0x100
	v_bfrev_b32_e32 v226, 40
	v_mov_b32_e32 v204, 0x3f317218
	v_mov_b64_e32 v[206:207], 0x260
	v_mov_b64_e32 v[208:209], 0x25f
	s_mov_b32 s79, 0x2aaaaaab
	s_mov_b32 s75, 0x41000000
	s_mov_b32 s83, 0x30000
	s_mov_b32 s68, 0x60000
	s_mov_b32 s70, 0x20000
	s_mov_b32 s72, 0x24000
	s_mov_b32 s60, 0x2c000
	s_mov_b32 s91, 0x6c000
	s_mov_b32 s56, 0x70000
	s_movk_i32 s71, 0x1246
	s_movk_i32 s54, 0x4918
	s_movk_i32 s25, 0xf05
	s_movk_i32 s55, 0xeff
	s_mov_b64 s[94:95], 0x80
	s_mov_b64 s[96:97], 0x100
	s_mov_b32 s80, 1.0
	s_mov_b32 s92, 0x3e0293ee
	s_mov_b32 s90, 1.0
	s_mov_b32 s34, 0x3b000000
	s_mov_b32 s37, 0
	v_writelane_b32 v255, s57, 4
	s_branch .LBB0_278

.LBB0_626:
	s_lshl_b32 s2, s9, 14
	s_add_i32 s2, s58, s2
	v_lshl_add_u64 v[2:3], s[60:61], 0, v[0:1]
	v_lshl_add_u64 v[2:3], v[2:3], 0, s[96:97]
	s_mov_b32 m0, s2
	v_mov_b32_e32 v15, v1
	global_load_lds_dwordx4 v[2:3], off
	v_lshl_add_u64 v[2:3], s[60:61], 0, v[14:15]
	v_lshl_add_u64 v[2:3], v[2:3], 0, s[96:97]
	s_add_i32 m0, s2, 0x2000
	s_cmp_lt_u32 s27, s59
	global_load_lds_dwordx4 v[2:3], off
	s_cselect_b64 vcc, -1, 0
	v_add_u32_e32 v2, 0x30000, v0
	v_add_u32_e32 v3, 0x30000, v14
	s_cmp_lg_u64 vcc, 0
	v_cndmask_b32_e32 v14, v14, v3, vcc
	v_cndmask_b32_e32 v0, v0, v2, vcc
	s_addc_u32 s27, s27, 0
	s_mul_i32 s2, s12, 0x6000
	v_add_u32_e32 v15, s2, v236
	v_add_u32_e32 v6, v15, v241
	ds_read_b128 v[2:5], v6
	ds_read_b128 v[6:9], v6 offset:12288
	v_exp_f32_e32 v12, v96
	s_waitcnt lgkmcnt(0)
	v_mfma_f32_32x32x16_bf16 v[112:127], v[2:5], v[144:147], 0
	v_mov_b32_e32 v2, v97
	v_exp_f32_e32 v96, v98
	v_exp_f32_e32 v97, v99
	v_exp_f32_e32 v13, v2
	v_mfma_f32_32x32x16_bf16 v[128:143], v[6:9], v[144:147], 0
	v_add_u32_e32 v2, v15, v242
	ds_read_b128 v[4:7], v2
	ds_read_b128 v[8:11], v2 offset:12288
	v_mov_b32_e32 v2, v100
	v_mov_b32_e32 v3, v101
	v_exp_f32_e32 v98, v2
	v_exp_f32_e32 v99, v3
	v_exp_f32_e32 v100, v102
	v_exp_f32_e32 v101, v103
	v_cvt_pk_bf16_f32 v2, v12, v13
	s_waitcnt lgkmcnt(0)
	v_mfma_f32_32x32x16_bf16 v[112:127], v[4:7], v[148:151], v[112:127]
	v_cvt_pk_bf16_f32 v3, v96, v97
	v_cvt_pk_bf16_f32 v4, v98, v99
	v_cvt_pk_bf16_f32 v5, v100, v101
	s_nop 0
	v_permlane32_swap_b32_e32 v2, v4
	v_permlane32_swap_b32_e32 v3, v5
	v_mfma_f32_32x32x16_bf16 v[128:143], v[8:11], v[148:151], v[128:143]
	v_add_u32_e32 v10, v15, v243
	ds_read_b128 v[6:9], v10
	v_add_f32_e64 v102, v214, v12
	v_add_f32_e64 v103, v215, v13
	ds_read_b128 v[10:13], v10 offset:12288
	v_exp_f32_e32 v104, v104
	v_exp_f32_e32 v105, v105
	s_waitcnt lgkmcnt(0)
	v_mfma_f32_32x32x16_bf16 v[112:127], v[6:9], v[152:155], v[112:127]
	v_add_f32_e64 v6, v96, v102
	v_add_f32_e64 v7, v97, v103
	v_exp_f32_e32 v102, v106
	v_exp_f32_e32 v103, v107
	v_pk_add_f32 v[6:7], v[98:99], v[6:7]
	s_nop 0
	v_pk_add_f32 v[6:7], v[100:101], v[6:7]
	s_nop 0
	v_pk_add_f32 v[100:101], v[104:105], v[6:7]
	v_mfma_f32_32x32x16_bf16 v[128:143], v[10:13], v[152:155], v[128:143]
	v_add_u32_e32 v6, v15, v244
	ds_read_b128 v[8:11], v6
	ds_read_b128 v[96:99], v6 offset:12288
	v_exp_f32_e32 v106, v108
	v_exp_f32_e32 v107, v109
	v_exp_f32_e32 v108, v110
	v_exp_f32_e32 v109, v111
	v_cvt_pk_bf16_f32 v6, v104, v105
	s_waitcnt lgkmcnt(0)
	v_mfma_f32_32x32x16_bf16 v[112:127], v[8:11], v[156:159], v[112:127]
	v_cvt_pk_bf16_f32 v7, v102, v103
	v_cvt_pk_bf16_f32 v8, v106, v107
	v_cvt_pk_bf16_f32 v9, v108, v109
	s_nop 0
	v_permlane32_swap_b32_e32 v6, v8
	v_permlane32_swap_b32_e32 v7, v9
	v_mfma_f32_32x32x16_bf16 v[128:143], v[96:99], v[156:159], v[128:143]
	v_add_u32_e32 v96, v15, v245
	ds_read_b128 v[10:13], v96
	ds_read_b128 v[96:99], v96 offset:12288
	v_exp_f32_e32 v104, v80
	s_waitcnt lgkmcnt(0)
	v_mfma_f32_32x32x16_bf16 v[112:127], v[10:13], v[160:163], v[112:127]
	v_exp_f32_e32 v105, v81
	v_exp_f32_e32 v110, v82
	v_exp_f32_e32 v111, v83
	v_mfma_f32_32x32x16_bf16 v[128:143], v[96:99], v[160:163], v[128:143]
	v_add_u32_e32 v80, v15, v246
	ds_read_b128 v[10:13], v80
	ds_read_b128 v[80:83], v80 offset:12288
	v_exp_f32_e32 v96, v84
	v_exp_f32_e32 v97, v85
	v_exp_f32_e32 v98, v86
	v_exp_f32_e32 v99, v87
	v_cvt_pk_bf16_f32 v192, v104, v105
	v_cvt_pk_bf16_f32 v193, v110, v111
	v_cvt_pk_bf16_f32 v194, v96, v97
	v_cvt_pk_bf16_f32 v195, v98, v99
	s_waitcnt lgkmcnt(0)
	v_mfma_f32_32x32x16_bf16 v[112:127], v[10:13], v[164:167], v[112:127]
	v_permlane32_swap_b32_e32 v192, v194
	v_permlane32_swap_b32_e32 v193, v195
	v_mfma_f32_32x32x16_bf16 v[128:143], v[80:83], v[164:167], v[128:143]
	v_add_u32_e32 v80, v15, v247
	ds_read_b128 v[10:13], v80
	ds_read_b128 v[80:83], v80 offset:12288
	s_waitcnt lgkmcnt(0)
	v_mfma_f32_32x32x16_bf16 v[112:127], v[10:13], v[168:171], v[112:127]
	v_exp_f32_e32 v10, v88
	v_exp_f32_e32 v11, v89
	v_exp_f32_e32 v12, v90
	v_exp_f32_e32 v13, v91
	v_mfma_f32_32x32x16_bf16 v[128:143], v[80:83], v[168:171], v[128:143]
	v_mov_b32_e32 v88, v92
	v_mov_b32_e32 v89, v93
	v_add_f32_e64 v92, v102, v100
	v_add_f32_e64 v93, v103, v101
	v_add_u32_e32 v84, v15, v248
	v_pk_add_f32 v[92:93], v[106:107], v[92:93]
	v_pk_add_f32 v[92:93], v[108:109], v[92:93]
	v_pk_add_f32 v[92:93], v[104:105], v[92:93]
	v_exp_f32_e32 v88, v88
	v_pk_add_f32 v[92:93], v[110:111], v[92:93]
	v_exp_f32_e32 v89, v89
	v_pk_add_f32 v[92:93], v[96:97], v[92:93]
	ds_read_b128 v[80:83], v84
	ds_read_b128 v[84:87], v84 offset:12288
	v_exp_f32_e32 v90, v94
	v_exp_f32_e32 v91, v95
	v_pk_add_f32 v[92:93], v[98:99], v[92:93]
	s_waitcnt lgkmcnt(0)
; #define SBAR() __builtin_amdgcn_sched_barrier(0)
; #define VSET(S, d0) do { constexpr int b_ = (d0) * 512; TRRD(S##l0, b_); TRRD(S##h0, b_ + 2048); TRRD(S##l1, b_ + 4096); TRRD(S##h1, b_ + 6144); \
;         TRRD(S##l2, b_ + 8192); TRRD(S##h2, b_ + 10240); TRRD(S##l3, b_ + 12288); TRRD(S##h3, b_ + 14336); } while (0)
; #define LWAIT(n) do { asm volatile("s_waitcnt lgkmcnt(" #n ")" ::: "memory"); SBAR(); } while (0)
; __device__ __forceinline__ void pv_tile(f32x16* o, unsigned vb, bf16x8 pa0, bf16x8 pa1, bf16x8 pa2, bf16x8 pa3) {
;     ...
;     s16x4 Al0, Al1, Al2, Al3, Ah0, Ah1, Ah2, Ah3, Bl0, Bl1, Bl2, Bl3, Bh0, Bh1, Bh2, Bh3;
;     VSET(A, 0);
;     VSET(B, 1); LWAIT(8); VMMA(A, 0); SBAR();
;     VSET(A, 2); LWAIT(8); VMMA(B, 1); SBAR();
;     VSET(B, 3); LWAIT(8); VMMA(A, 2); SBAR();
;     LWAIT(0); VMMA(B, 3);
	v_mfma_f32_32x32x16_bf16 v[112:127], v[80:83], v[172:175], v[112:127]
	v_add_f32_e64 v92, v10, v92
	v_add_f32_e64 v93, v11, v93
	v_cvt_pk_bf16_f32 v10, v10, v11
	v_add_f32_e64 v92, v12, v92
	v_add_f32_e64 v93, v13, v93
	v_cvt_pk_bf16_f32 v11, v12, v13
	v_pk_add_f32 v[92:93], v[88:89], v[92:93]
	v_cvt_pk_bf16_f32 v12, v88, v89
	v_pk_add_f32 v[214:215], v[90:91], v[92:93]
	v_cvt_pk_bf16_f32 v13, v90, v91
	v_permlane32_swap_b32_e32 v10, v12
	s_nop 0
	v_permlane32_swap_b32_e32 v11, v13
	v_mfma_f32_32x32x16_bf16 v[128:143], v[84:87], v[172:175], v[128:143]
	v_add_u32_e32 v92, v15, v249
	v_add_u32_e32 v93, v15, v250
	v_add_u32_e32 v94, v15, v251
	v_add_u32_e32 v95, v15, v252
	ds_read_b128 v[96:99], v92
	ds_read_b128 v[100:103], v92 offset:12288
	ds_read_b128 v[104:107], v93
	ds_read_b128 v[108:111], v93 offset:12288
	ds_read_b128 v[84:87], v94
	ds_read_b128 v[88:91], v94 offset:12288
	ds_read_b128 v[80:83], v95
	ds_read_b128 v[222:225], v95 offset:12288
	s_waitcnt lgkmcnt(7)
	v_mfma_f32_32x32x16_bf16 v[112:127], v[96:99], v[176:179], v[112:127]
	s_waitcnt lgkmcnt(6)
	v_mfma_f32_32x32x16_bf16 v[128:143], v[100:103], v[176:179], v[128:143]
	s_waitcnt lgkmcnt(5)
	v_mfma_f32_32x32x16_bf16 v[112:127], v[104:107], v[180:183], v[112:127]
	s_waitcnt lgkmcnt(4)
	v_mfma_f32_32x32x16_bf16 v[128:143], v[108:111], v[180:183], v[128:143]
	s_waitcnt lgkmcnt(3)
	v_mfma_f32_32x32x16_bf16 v[112:127], v[84:87], v[184:187], v[112:127]
	s_waitcnt lgkmcnt(2)
	v_mfma_f32_32x32x16_bf16 v[128:143], v[88:91], v[184:187], v[128:143]
	s_waitcnt lgkmcnt(1)
	v_mfma_f32_32x32x16_bf16 v[96:111], v[80:83], v[188:191], v[112:127]
	s_waitcnt lgkmcnt(0)
	v_mfma_f32_32x32x16_bf16 v[80:95], v[222:225], v[188:191], v[128:143]
	v_lshl_add_u32 v15, s7, 14, v237
	ds_read_b64_tr_b16 v[112:113], v15 offset:0
	ds_read_b64_tr_b16 v[114:115], v15 offset:0x800
	ds_read_b64_tr_b16 v[116:117], v15 offset:0x1000
	ds_read_b64_tr_b16 v[118:119], v15 offset:0x1800
	ds_read_b64_tr_b16 v[120:121], v15 offset:0x2000
	ds_read_b64_tr_b16 v[122:123], v15 offset:0x2800
	ds_read_b64_tr_b16 v[124:125], v15 offset:0x3000
	ds_read_b64_tr_b16 v[126:127], v15 offset:0x3800
	ds_read_b64_tr_b16 v[128:129], v15 offset:0x200
	ds_read_b64_tr_b16 v[130:131], v15 offset:0xa00
	ds_read_b64_tr_b16 v[132:133], v15 offset:0x1200
	ds_read_b64_tr_b16 v[134:135], v15 offset:0x1a00
	ds_read_b64_tr_b16 v[136:137], v15 offset:0x2200
	ds_read_b64_tr_b16 v[138:139], v15 offset:0x2a00
	ds_read_b64_tr_b16 v[140:141], v15 offset:0x3200
	ds_read_b64_tr_b16 v[142:143], v15 offset:0x3a00
	s_waitcnt lgkmcnt(8)
	s_nop 0
	v_mfma_f32_32x32x16_bf16 v[64:79], v[2:5], v[112:115], v[64:79]
	v_mfma_f32_32x32x16_bf16 v[64:79], v[6:9], v[116:119], v[64:79]
	v_mfma_f32_32x32x16_bf16 v[64:79], v[192:195], v[120:123], v[64:79]
	v_mfma_f32_32x32x16_bf16 v[64:79], v[10:13], v[124:127], v[64:79]
	ds_read_b64_tr_b16 v[112:113], v15 offset:0x400
	ds_read_b64_tr_b16 v[114:115], v15 offset:0xc00
	ds_read_b64_tr_b16 v[116:117], v15 offset:0x1400
	ds_read_b64_tr_b16 v[118:119], v15 offset:0x1c00
	ds_read_b64_tr_b16 v[120:121], v15 offset:0x2400
	ds_read_b64_tr_b16 v[122:123], v15 offset:0x2c00
	ds_read_b64_tr_b16 v[124:125], v15 offset:0x3400
	ds_read_b64_tr_b16 v[126:127], v15 offset:0x3c00
	s_waitcnt lgkmcnt(8)
	v_mfma_f32_32x32x16_bf16 v[48:63], v[2:5], v[128:131], v[48:63]
	v_mfma_f32_32x32x16_bf16 v[48:63], v[6:9], v[132:135], v[48:63]
	v_mfma_f32_32x32x16_bf16 v[48:63], v[192:195], v[136:139], v[48:63]
	v_mfma_f32_32x32x16_bf16 v[48:63], v[10:13], v[140:143], v[48:63]
	ds_read_b64_tr_b16 v[128:129], v15 offset:0x600
	ds_read_b64_tr_b16 v[130:131], v15 offset:0xe00
	ds_read_b64_tr_b16 v[132:133], v15 offset:0x1600
	ds_read_b64_tr_b16 v[134:135], v15 offset:0x1e00
	ds_read_b64_tr_b16 v[136:137], v15 offset:0x2600
	ds_read_b64_tr_b16 v[138:139], v15 offset:0x2e00
	ds_read_b64_tr_b16 v[140:141], v15 offset:0x3600
	ds_read_b64_tr_b16 v[142:143], v15 offset:0x3e00
	s_waitcnt lgkmcnt(8)
	v_mfma_f32_32x32x16_bf16 v[32:47], v[2:5], v[112:115], v[32:47]
	v_mfma_f32_32x32x16_bf16 v[32:47], v[6:9], v[116:119], v[32:47]
	v_mfma_f32_32x32x16_bf16 v[32:47], v[192:195], v[120:123], v[32:47]
	v_mfma_f32_32x32x16_bf16 v[32:47], v[10:13], v[124:127], v[32:47]
	s_waitcnt lgkmcnt(0)
	v_mfma_f32_32x32x16_bf16 v[16:31], v[2:5], v[128:131], v[16:31]
	s_waitcnt vmcnt(5)
	s_barrier
	s_add_i32 s13, s13, -1
	s_cmp_eq_u32 s13, 0
	v_mfma_f32_32x32x16_bf16 v[16:31], v[6:9], v[132:135], v[16:31]
	v_mfma_f32_32x32x16_bf16 v[16:31], v[192:195], v[136:139], v[16:31]
	v_mfma_f32_32x32x16_bf16 v[16:31], v[10:13], v[140:143], v[16:31]
	s_cbranch_scc1 .LBB0_629
	s_mov_b32 s2, s12
	s_mov_b32 s12, s9
	s_mov_b32 s9, s7
	s_branch .LBB0_624

.LBB0_821:
	s_mov_b32 s12, s14
	s_lshl_b32 s14, s2, 14
	s_mov_b32 s63, s70
	s_mov_b32 s70, s2
	s_add_i32 s2, s9, s14
	s_add_i32 m0, s2, 0xc000
	v_add_u32_e32 v0, 0x98000, v163
	global_load_lds_dwordx4 v165, s[60:61]
	s_add_i32 m0, s2, 0xe000
	s_cmp_lt_u32 s83, s57
	s_cselect_b64 s[18:19], -1, 0
	s_and_b64 s[34:35], s[18:19], exec
	s_cselect_b32 s2, 0x98000, 0
	s_cmp_lg_u64 s[18:19], 0
	global_load_lds_dwordx4 v164, s[60:61]
	v_add_u32_e32 v164, s2, v164
	v_add_u32_e32 v165, s2, v165
	s_addc_u32 s83, s83, 0
	s_lshl_b32 s2, s63, 14
	s_add_i32 s2, s9, s2
	s_mov_b32 m0, s2
	v_add_u32_e32 v98, 0x98000, v162
	global_load_lds_dwordx4 v163, s[76:77]
	s_add_i32 m0, s2, 0x2000
	s_cmp_lt_u32 s62, s57
	global_load_lds_dwordx4 v162, s[76:77]
	s_cselect_b64 vcc, -1, 0
	s_cmp_lg_u64 vcc, 0
	v_cndmask_b32_e32 v162, v162, v98, vcc
	v_cndmask_b32_e32 v163, v163, v0, vcc
	s_addc_u32 s62, s62, 0
	v_lshl_add_u32 v0, s12, 14, v160
	v_add_u32_e32 v102, v0, v166
	v_exp_f32_e32 v150, v82
	v_exp_f32_e32 v151, v83
	v_exp_f32_e32 v152, v84
	v_exp_f32_e32 v153, v85
	ds_read_b128 v[98:101], v102
	ds_read_b128 v[114:117], v102 offset:8192
	v_exp_f32_e32 v170, v86
	v_exp_f32_e32 v171, v87
	v_exp_f32_e32 v172, v88
	v_exp_f32_e32 v173, v89
	v_cvt_pk_bf16_f32 v146, v150, v151
	v_cvt_pk_bf16_f32 v147, v152, v153
	v_cvt_pk_bf16_f32 v148, v170, v171
	v_cvt_pk_bf16_f32 v149, v172, v173
	s_waitcnt lgkmcnt(0)
	v_mfma_f32_32x32x16_bf16 v[98:113], v[98:101], v[130:133], 0
	v_permlane32_swap_b32_e32 v146, v148
	v_permlane32_swap_b32_e32 v147, v149
	v_mfma_f32_32x32x16_bf16 v[114:129], v[114:117], v[130:133], 0
	v_add_u32_e32 v86, v0, v167
	v_mov_b32_e32 v174, v92
	v_mov_b32_e32 v175, v93
	ds_read_b128 v[82:85], v86
	ds_read_b128 v[86:89], v86 offset:8192
	v_exp_f32_e32 v90, v90
	v_exp_f32_e32 v91, v91
	v_pk_add_f32 v[92:93], v[156:157], v[150:151]
	v_exp_f32_e32 v156, v174
	v_exp_f32_e32 v157, v175
	v_exp_f32_e32 v174, v94
	v_exp_f32_e32 v175, v95
	v_exp_f32_e32 v176, v96
	v_exp_f32_e32 v177, v97
	v_pk_add_f32 v[92:93], v[152:153], v[92:93]
	v_cvt_pk_bf16_f32 v150, v90, v91
	v_pk_add_f32 v[92:93], v[170:171], v[92:93]
	v_cvt_pk_bf16_f32 v151, v156, v157
	v_pk_add_f32 v[92:93], v[172:173], v[92:93]
	v_cvt_pk_bf16_f32 v152, v174, v175
	v_pk_add_f32 v[92:93], v[90:91], v[92:93]
	v_cvt_pk_bf16_f32 v153, v176, v177
	s_waitcnt lgkmcnt(0)
	v_mfma_f32_32x32x16_bf16 v[98:113], v[82:85], v[134:137], v[98:113]
	v_permlane32_swap_b32_e32 v150, v152
	v_permlane32_swap_b32_e32 v151, v153
	v_mfma_f32_32x32x16_bf16 v[114:129], v[86:89], v[134:137], v[114:129]
	v_add_u32_e32 v86, v0, v168
	v_exp_f32_e32 v178, v66
	v_exp_f32_e32 v179, v67
	v_exp_f32_e32 v180, v68
	v_exp_f32_e32 v181, v69
	ds_read_b128 v[82:85], v86
	ds_read_b128 v[86:89], v86 offset:8192
	v_exp_f32_e32 v182, v70
	v_exp_f32_e32 v183, v71
	v_exp_f32_e32 v184, v72
	v_exp_f32_e32 v185, v73
	v_cvt_pk_bf16_f32 v170, v178, v179
	v_cvt_pk_bf16_f32 v171, v180, v181
	v_cvt_pk_bf16_f32 v172, v182, v183
	v_cvt_pk_bf16_f32 v173, v184, v185
	s_waitcnt lgkmcnt(0)
	v_mfma_f32_32x32x16_bf16 v[98:113], v[82:85], v[138:141], v[98:113]
	v_permlane32_swap_b32_e32 v170, v172
	v_permlane32_swap_b32_e32 v171, v173
	v_mfma_f32_32x32x16_bf16 v[114:129], v[86:89], v[138:141], v[114:129]
	v_add_u32_e32 v0, v0, v169
	v_add_f32_e64 v156, v156, v92
	v_add_f32_e64 v157, v157, v93
	ds_read_b128 v[232:235], v0
	ds_read_b128 v[236:239], v0 offset:8192
	v_mov_b32_e32 v193, v81
	v_pk_add_f32 v[248:249], v[174:175], v[156:157]
	v_exp_f32_e32 v240, v74
	v_pk_add_f32 v[248:249], v[176:177], v[248:249]
	v_exp_f32_e32 v241, v75
	v_pk_add_f32 v[248:249], v[178:179], v[248:249]
	s_waitcnt lgkmcnt(0)
; #define SBAR() __builtin_amdgcn_sched_barrier(0)
; #define VSET(S, d0) do { constexpr int b_ = (d0) * 512; TRRD(S##l0, b_); TRRD(S##h0, b_ + 2048); TRRD(S##l1, b_ + 4096); TRRD(S##h1, b_ + 6144); \
;         TRRD(S##l2, b_ + 8192); TRRD(S##h2, b_ + 10240); TRRD(S##l3, b_ + 12288); TRRD(S##h3, b_ + 14336); } while (0)
; #define LWAIT(n) do { asm volatile("s_waitcnt lgkmcnt(" #n ")" ::: "memory"); SBAR(); } while (0)
; __device__ __forceinline__ void pv_tile(f32x16* o, unsigned vb, bf16x8 pa0, bf16x8 pa1, bf16x8 pa2, bf16x8 pa3) {
;     ...
;     s16x4 Al0, Al1, Al2, Al3, Ah0, Ah1, Ah2, Ah3, Bl0, Bl1, Bl2, Bl3, Bh0, Bh1, Bh2, Bh3;
;     VSET(A, 0);
;     VSET(B, 1); LWAIT(8); VMMA(A, 0); SBAR();
;     VSET(A, 2); LWAIT(8); VMMA(B, 1); SBAR();
;     VSET(B, 3); LWAIT(8); VMMA(A, 2); SBAR();
;     LWAIT(0); VMMA(B, 3);
	v_mfma_f32_32x32x16_bf16 v[82:97], v[232:235], v[142:145], v[98:113]
	v_exp_f32_e32 v242, v76
	v_exp_f32_e32 v243, v77
	v_pk_add_f32 v[250:251], v[180:181], v[248:249]
	v_exp_f32_e32 v244, v78
	v_exp_f32_e32 v245, v79
	v_pk_add_f32 v[248:249], v[182:183], v[250:251]
	v_exp_f32_e32 v246, v80
	v_mfma_f32_32x32x16_bf16 v[66:81], v[236:239], v[142:145], v[114:129]
	v_exp_f32_e32 v247, v193
	v_pk_add_f32 v[248:249], v[184:185], v[248:249]
	v_cvt_pk_bf16_f32 v98, v240, v241
	v_pk_add_f32 v[250:251], v[240:241], v[248:249]
	v_cvt_pk_bf16_f32 v99, v242, v243
	v_pk_add_f32 v[250:251], v[242:243], v[250:251]
	v_cvt_pk_bf16_f32 v100, v244, v245
	v_pk_add_f32 v[250:251], v[244:245], v[250:251]
	v_cvt_pk_bf16_f32 v101, v246, v247
	v_pk_add_f32 v[156:157], v[246:247], v[250:251]
	v_permlane32_swap_b32_e32 v98, v100
	v_permlane32_swap_b32_e32 v99, v101
	v_add_u32_e32 v0, s14, v161
	ds_read_b64_tr_b16 v[102:103], v0 offset:0
	ds_read_b64_tr_b16 v[104:105], v0 offset:0x800
	ds_read_b64_tr_b16 v[106:107], v0 offset:0x1000
	ds_read_b64_tr_b16 v[108:109], v0 offset:0x1800
	ds_read_b64_tr_b16 v[110:111], v0 offset:0x2000
	ds_read_b64_tr_b16 v[112:113], v0 offset:0x2800
	ds_read_b64_tr_b16 v[114:115], v0 offset:0x3000
	ds_read_b64_tr_b16 v[116:117], v0 offset:0x3800
	ds_read_b64_tr_b16 v[118:119], v0 offset:0x200
	ds_read_b64_tr_b16 v[120:121], v0 offset:0xa00
	ds_read_b64_tr_b16 v[122:123], v0 offset:0x1200
	ds_read_b64_tr_b16 v[124:125], v0 offset:0x1a00
	ds_read_b64_tr_b16 v[126:127], v0 offset:0x2200
	ds_read_b64_tr_b16 v[128:129], v0 offset:0x2a00
	ds_read_b64_tr_b16 v[174:175], v0 offset:0x3200
	ds_read_b64_tr_b16 v[176:177], v0 offset:0x3a00
	s_waitcnt lgkmcnt(8)
	s_nop 0
	v_mfma_f32_32x32x16_bf16 v[50:65], v[146:149], v[102:105], v[50:65]
	v_mfma_f32_32x32x16_bf16 v[50:65], v[150:153], v[106:109], v[50:65]
	v_mfma_f32_32x32x16_bf16 v[50:65], v[170:173], v[110:113], v[50:65]
	v_mfma_f32_32x32x16_bf16 v[50:65], v[98:101], v[114:117], v[50:65]
	ds_read_b64_tr_b16 v[102:103], v0 offset:0x400
	ds_read_b64_tr_b16 v[104:105], v0 offset:0xc00
	ds_read_b64_tr_b16 v[106:107], v0 offset:0x1400
	ds_read_b64_tr_b16 v[108:109], v0 offset:0x1c00
	ds_read_b64_tr_b16 v[110:111], v0 offset:0x2400
	ds_read_b64_tr_b16 v[112:113], v0 offset:0x2c00
	ds_read_b64_tr_b16 v[114:115], v0 offset:0x3400
	ds_read_b64_tr_b16 v[116:117], v0 offset:0x3c00
	s_waitcnt lgkmcnt(8)
	v_mfma_f32_32x32x16_bf16 v[34:49], v[146:149], v[118:121], v[34:49]
	v_mfma_f32_32x32x16_bf16 v[34:49], v[150:153], v[122:125], v[34:49]
	v_mfma_f32_32x32x16_bf16 v[34:49], v[170:173], v[126:129], v[34:49]
	v_mfma_f32_32x32x16_bf16 v[34:49], v[98:101], v[174:177], v[34:49]
	ds_read_b64_tr_b16 v[118:119], v0 offset:0x600
	ds_read_b64_tr_b16 v[120:121], v0 offset:0xe00
	ds_read_b64_tr_b16 v[122:123], v0 offset:0x1600
	ds_read_b64_tr_b16 v[124:125], v0 offset:0x1e00
	ds_read_b64_tr_b16 v[126:127], v0 offset:0x2600
	ds_read_b64_tr_b16 v[128:129], v0 offset:0x2e00
	ds_read_b64_tr_b16 v[174:175], v0 offset:0x3600
	ds_read_b64_tr_b16 v[176:177], v0 offset:0x3e00
	s_waitcnt lgkmcnt(8)
	v_mfma_f32_32x32x16_bf16 v[18:33], v[146:149], v[102:105], v[18:33]
	v_mfma_f32_32x32x16_bf16 v[18:33], v[150:153], v[106:109], v[18:33]
	v_mfma_f32_32x32x16_bf16 v[18:33], v[170:173], v[110:113], v[18:33]
	v_mfma_f32_32x32x16_bf16 v[18:33], v[98:101], v[114:117], v[18:33]
	s_waitcnt lgkmcnt(0)
	v_mfma_f32_32x32x16_bf16 v[2:17], v[146:149], v[118:121], v[2:17]
	s_waitcnt vmcnt(4)
	s_barrier
	s_add_i32 s13, s13, -1
	s_cmp_lg_u32 s13, 0
	s_mov_b32 s2, s12
	s_mov_b32 s14, s63
	v_mfma_f32_32x32x16_bf16 v[2:17], v[150:153], v[122:125], v[2:17]
	v_mfma_f32_32x32x16_bf16 v[2:17], v[170:173], v[126:129], v[2:17]
	v_mfma_f32_32x32x16_bf16 v[2:17], v[98:101], v[174:177], v[2:17]
	s_cbranch_scc1 .LBB0_821
	s_branch .LBB0_823

; __device__ __forceinline__ void unpack8(const u32x4 w, float* f) { f[0] = bflo(w.x); f[1] = bfhi(w.x); f[2] = bflo(w.y); f[3] = bfhi(w.y); f[4] = bflo(w.z); f[5] = bfhi(w.z); f[6] = bflo(w.w); f[7] = bfhi(w.w); }
; __device__ __forceinline__ u32x4 pack8f(const float* f) { u32x4 w; w.x = cvtpk(f[0], f[1]); w.y = cvtpk(f[2], f[3]); w.z = cvtpk(f[4], f[5]); w.w = cvtpk(f[6], f[7]); return w; }
; __device__ __forceinline__ void post_mla_row(ArgsP a, int l, int row, int lane) {
;     ...
;     {
;         const int g = lane >> 3, j = lane & 7; const bool act = g < 6;
;         float x[8]; unpack8(ld_r, x);
;         float ss = 0.f;
; #pragma unroll
;         for (int i = 0; i < 8; ++i) ss += x[i] * x[i];
;         ss += __shfl_xor(ss, 1); ss += __shfl_xor(ss, 2); ss += __shfl_xor(ss, 4);
;         const float rstd = rsqrtf(ss * (1.0f / 64.0f) + RMS_EPS);
;         const float* gn = a->in[I_MQN] + l * 192 + 8 * j;
;         const float* cp = (const float*)(ws + WS_COSM) + row * 32 + 8 * (j & 3); const float* sp = (const float*)(ws + WS_SINM) + row * 32 + 8 * (j & 3);
;         float y[8];
; #pragma unroll
;         for (int i = 0; i < 8; ++i) {
;             const float mine = x[i] * rstd * gn[i]; const float other = __shfl_xor(mine, 4);
;             y[i] = (j < 4) ? (mine * cp[i] - other * sp[i]) : (mine * cp[i] + other * sp[i]);
;         }
;         if (act) *(u32x4*)(Q + g * 192 + 8 * j) = pack8f(y);
;     }
.LBB0_1350:
	v_lshl_add_u64 v[2:3], s[66:67], 0, v[38:39]
	global_load_dwordx4 v[48:51], v[2:3], off
	global_load_dwordx4 v[52:55], v[18:19], off
	global_load_dwordx4 v[56:59], v[18:19], off offset:16
	v_lshl_add_u64 v[46:47], s[66:67], 0, v[36:37]
	v_lshl_add_u64 v[42:43], s[66:67], 0, v[34:35]
	v_lshl_add_u64 v[44:45], s[66:67], 0, v[30:31]
	v_lshl_add_u64 v[40:41], s[66:67], 0, v[28:29]
	global_load_dwordx4 v[14:17], v[46:47], off
	global_load_dwordx4 v[6:9], v[42:43], off
	s_waitcnt lgkmcnt(0)
	global_load_dwordx4 v[10:13], v[44:45], off
	global_load_dwordx4 v[2:5], v[40:41], off
	s_waitcnt vmcnt(0)
	v_lshlrev_b32_e32 v62, 16, v48
	v_and_b32_e32 v63, 0xffff0000, v48
	v_lshlrev_b32_e32 v48, 16, v49
	v_and_b32_e32 v49, 0xffff0000, v49
	v_pk_mul_f32 v[70:71], v[62:63], v[62:63]
	v_pk_mul_f32 v[72:73], v[48:49], v[48:49]
	v_add_f32_e32 v0, v70, v71
	v_lshlrev_b32_e32 v68, 16, v50
	v_and_b32_e32 v69, 0xffff0000, v50
	v_add_f32_e32 v0, v72, v0
	v_pk_mul_f32 v[74:75], v[68:69], v[68:69]
	v_add_f32_e32 v0, v73, v0
	v_lshlrev_b32_e32 v60, 16, v51
	v_and_b32_e32 v61, 0xffff0000, v51
	v_add_f32_e32 v0, v74, v0
	v_pk_mul_f32 v[50:51], v[60:61], v[60:61]
	v_add_f32_e32 v0, v75, v0
	v_add_f32_e32 v0, v50, v0
	v_add_f32_e32 v0, v51, v0
	ds_bpermute_b32 v50, v64, v0
	s_waitcnt lgkmcnt(0)
	v_add_f32_e32 v0, v0, v50
	ds_bpermute_b32 v50, v65, v0
	s_waitcnt lgkmcnt(0)
	v_add_f32_e32 v0, v0, v50
	ds_bpermute_b32 v50, v66, v0
	s_waitcnt lgkmcnt(0)
	v_add_f32_e32 v0, v0, v50
	v_fmamk_f32 v0, v0, 0x3c800000, v198
	v_mul_f32_e32 v50, 0x4b800000, v0
	v_cmp_gt_f32_e64 s[8:9], s16, v0
	s_nop 1
	v_cndmask_b32_e64 v0, v0, v50, s[8:9]
	v_rsq_f32_e32 v0, v0
	s_nop 0
	v_mul_f32_e32 v50, 0x45800000, v0
	v_cndmask_b32_e64 v0, v0, v50, s[8:9]
	v_mul_f32_e32 v0, 0x3dd53b94, v0
	v_pk_mul_f32 v[50:51], v[0:1], v[62:63] op_sel_hi:[0,1]
	v_pk_mul_f32 v[62:63], v[0:1], v[48:49] op_sel_hi:[0,1]
	v_pk_mul_f32 v[68:69], v[0:1], v[68:69] op_sel_hi:[0,1]
	v_pk_mul_f32 v[60:61], v[0:1], v[60:61] op_sel_hi:[0,1]
	v_pk_mul_f32 v[48:49], v[52:53], v[50:51]
	v_pk_mul_f32 v[50:51], v[54:55], v[62:63]
	v_pk_mul_f32 v[52:53], v[56:57], v[68:69]
	v_pk_mul_f32 v[54:55], v[60:61], v[58:59]
	ds_bpermute_b32 v56, v66, v48
	ds_bpermute_b32 v57, v66, v49
	ds_bpermute_b32 v58, v66, v50
	ds_bpermute_b32 v59, v66, v51
	ds_bpermute_b32 v60, v66, v52
	ds_bpermute_b32 v61, v66, v53
	ds_bpermute_b32 v62, v66, v54
	ds_bpermute_b32 v63, v66, v55
	s_and_saveexec_b64 s[8:9], vcc
	s_cbranch_execz .LBB0_1352
	s_ashr_i32 s11, s10, 31
	s_lshl_b64 s[12:13], s[10:11], 2
	v_lshl_add_u64 v[72:73], v[20:21], 0, s[12:13]
	global_load_dwordx4 v[68:71], v[72:73], off offset:16
	s_nop 0
	global_load_dwordx4 v[72:75], v[72:73], off
	v_lshl_add_u64 v[80:81], v[22:23], 0, s[12:13]
	global_load_dwordx4 v[76:79], v[80:81], off offset:16
	s_nop 0
	global_load_dwordx4 v[80:83], v[80:81], off
	s_waitcnt vmcnt(3) lgkmcnt(0)
	v_pk_mul_f32 v[62:63], v[70:71], v[62:63]
	v_pk_mul_f32 v[60:61], v[68:69], v[60:61]
	s_waitcnt vmcnt(2)
	v_pk_mul_f32 v[58:59], v[74:75], v[58:59]
	v_pk_mul_f32 v[56:57], v[72:73], v[56:57]
	v_cndmask_b32_e64 v63, v63, -v63, s[4:5]
	v_cndmask_b32_e64 v62, v62, -v62, s[4:5]
	v_cndmask_b32_e64 v61, v61, -v61, s[4:5]
	v_cndmask_b32_e64 v60, v60, -v60, s[4:5]
	v_cndmask_b32_e64 v59, v59, -v59, s[4:5]
	v_cndmask_b32_e64 v58, v58, -v58, s[4:5]
	v_cndmask_b32_e64 v57, v57, -v57, s[4:5]
	v_cndmask_b32_e64 v56, v56, -v56, s[4:5]
	s_waitcnt vmcnt(1)
	v_pk_fma_f32 v[54:55], v[54:55], v[78:79], v[62:63]
	v_pk_fma_f32 v[52:53], v[52:53], v[76:77], v[60:61]
	s_waitcnt vmcnt(0)
	v_pk_fma_f32 v[50:51], v[50:51], v[82:83], v[58:59]
	v_pk_fma_f32 v[48:49], v[48:49], v[80:81], v[56:57]
	s_nop 0
	v_cvt_pk_bf16_f32 v48, v48, v49
	v_cvt_pk_bf16_f32 v49, v50, v51
	v_cvt_pk_bf16_f32 v50, v52, v53
	v_cvt_pk_bf16_f32 v51, v54, v55
	v_lshl_add_u64 v[52:53], s[66:67], 0, v[32:33]
	global_store_dwordx4 v[52:53], v[48:51], off
; __device__ __forceinline__ void unpack8(const u32x4 w, float* f) { f[0] = bflo(w.x); f[1] = bfhi(w.x); f[2] = bflo(w.y); f[3] = bfhi(w.y); f[4] = bflo(w.z); f[5] = bfhi(w.z); f[6] = bflo(w.w); f[7] = bfhi(w.w); }
; __device__ __forceinline__ u32x4 pack8f(const float* f) { u32x4 w; w.x = cvtpk(f[0], f[1]); w.y = cvtpk(f[2], f[3]); w.z = cvtpk(f[4], f[5]); w.w = cvtpk(f[6], f[7]); return w; }
; __device__ __forceinline__ void post_mla_row(ArgsP a, int l, int row, int lane) {
;     ...
; #pragma unroll
;     for (int p = 0; p < 2; ++p) {
;         const int g = 4 * p + (lane >> 4), j = lane & 15; const bool act = g < 6; const int gg = act ? g : 0;
;         {
;             bf16_t* ptr = Q + gg * 192 + 64 + 8 * j;
;             float x[8]; unpack8(p == 0 ? ld_qn0 : ld_qn1, x);
;             float ss = 0.f;
; #pragma unroll
;             for (int i = 0; i < 8; ++i) ss += x[i] * x[i];
;             ss += __shfl_xor(ss, 1); ss += __shfl_xor(ss, 2); ss += __shfl_xor(ss, 4); ss += __shfl_xor(ss, 8);
;             const float rstd = rsqrtf(ss * (1.0f / 128.0f) + RMS_EPS);
;             const float* gn = a->in[I_MQN] + l * 192 + 64 + 8 * j;
; #pragma unroll
;             for (int i = 0; i < 8; ++i) x[i] = x[i] * rstd * gn[i];
;             if (act) *(u32x4*)ptr = pack8f(x);
;         }
;         {
;             bf16_t* ptr = KV + gg * 256 + 8 * j;
;             float x[8]; unpack8(p == 0 ? ld_kn0 : ld_kn1, x);
;             float ss = 0.f;
; #pragma unroll
;             for (int i = 0; i < 8; ++i) ss += x[i] * x[i];
;             ss += __shfl_xor(ss, 1); ss += __shfl_xor(ss, 2); ss += __shfl_xor(ss, 4); ss += __shfl_xor(ss, 8);
;             const float rstd = rsqrtf(ss * (1.0f / 128.0f) + RMS_EPS);
;             const float* gn = a->in[I_MKN] + l * 192 + 64 + 8 * j;
; #pragma unroll
;             for (int i = 0; i < 8; ++i) x[i] = x[i] * rstd * gn[i];
;             if (act) *(u32x4*)ptr = pack8f(x);
;         }
;     }
.LBB0_1352:
	s_or_b64 exec, exec, s[8:9]
	global_load_dwordx4 v[48:51], v[24:25], off offset:272
	global_load_dwordx4 v[52:55], v[24:25], off offset:256
	v_and_b32_e32 v71, 0xffff0000, v14
	v_and_b32_e32 v81, 0xffff0000, v10
	s_waitcnt lgkmcnt(1)
	v_lshlrev_b32_e32 v62, 16, v15
	s_waitcnt lgkmcnt(0)
	v_and_b32_e32 v63, 0xffff0000, v15
	v_lshlrev_b32_e32 v70, 16, v14
	v_lshlrev_b32_e32 v76, 16, v11
	v_and_b32_e32 v77, 0xffff0000, v11
	v_lshlrev_b32_e32 v80, 16, v10
	v_mov_b32_e32 v82, v81
	v_mov_b32_e32 v83, v71
	v_pk_mul_f32 v[68:69], v[62:63], v[62:63]
	v_pk_mul_f32 v[78:79], v[76:77], v[76:77]
	v_mov_b32_e32 v10, v80
	v_mov_b32_e32 v11, v70
	v_pk_mul_f32 v[82:83], v[82:83], v[82:83]
	v_lshlrev_b32_e32 v60, 16, v16
	v_and_b32_e32 v61, 0xffff0000, v16
	v_lshlrev_b32_e32 v74, 16, v12
	v_and_b32_e32 v75, 0xffff0000, v12
	v_pk_fma_f32 v[10:11], v[10:11], v[10:11], v[82:83]
	v_mov_b32_e32 v82, v78
	v_mov_b32_e32 v83, v68
	v_lshlrev_b32_e32 v56, 16, v17
	v_and_b32_e32 v57, 0xffff0000, v17
	v_pk_mul_f32 v[16:17], v[60:61], v[60:61]
	v_lshlrev_b32_e32 v72, 16, v13
	v_and_b32_e32 v73, 0xffff0000, v13
	v_pk_mul_f32 v[12:13], v[74:75], v[74:75]
	v_pk_add_f32 v[10:11], v[82:83], v[10:11]
	v_mov_b32_e32 v68, v79
	v_pk_add_f32 v[10:11], v[68:69], v[10:11]
	v_mov_b32_e32 v68, v12
	v_mov_b32_e32 v69, v16
	v_pk_mul_f32 v[58:59], v[56:57], v[56:57]
	v_pk_mul_f32 v[14:15], v[72:73], v[72:73]
	v_pk_add_f32 v[10:11], v[68:69], v[10:11]
	v_mov_b32_e32 v16, v13
	v_pk_add_f32 v[10:11], v[16:17], v[10:11]
	v_mov_b32_e32 v12, v14
	v_mov_b32_e32 v13, v58
	v_pk_add_f32 v[10:11], v[12:13], v[10:11]
	v_mov_b32_e32 v58, v15
	v_pk_add_f32 v[10:11], v[58:59], v[10:11]
	ds_bpermute_b32 v13, v64, v11
	ds_bpermute_b32 v12, v64, v10
	s_brev_b32 s2, 60
	s_waitcnt lgkmcnt(0)
	v_pk_add_f32 v[10:11], v[10:11], v[12:13]
	ds_bpermute_b32 v13, v65, v11
	ds_bpermute_b32 v12, v65, v10
	s_waitcnt lgkmcnt(0)
	v_pk_add_f32 v[10:11], v[10:11], v[12:13]
	ds_bpermute_b32 v13, v66, v11
	ds_bpermute_b32 v12, v66, v10
	s_waitcnt lgkmcnt(0)
	v_pk_add_f32 v[10:11], v[10:11], v[12:13]
	ds_bpermute_b32 v13, v67, v11
	ds_bpermute_b32 v12, v67, v10
	s_waitcnt lgkmcnt(0)
	v_pk_add_f32 v[10:11], v[10:11], v[12:13]
	s_nop 0
	v_pk_fma_f32 v[14:15], v[10:11], s[2:3], v[198:199] op_sel_hi:[1,0,0]
	s_nop 0
	v_mul_f32_e32 v0, 0x4b800000, v15
	v_cmp_gt_f32_e64 s[8:9], s16, v15
	s_nop 1
	v_cndmask_b32_e64 v0, v15, v0, s[8:9]
	v_rsq_f32_e32 v0, v0
	s_nop 0
	v_mul_f32_e32 v10, 0x45800000, v0
	v_cndmask_b32_e64 v0, v0, v10, s[8:9]
	v_mul_f32_e32 v0, 0x3dd53b94, v0
	v_pk_mul_f32 v[10:11], v[0:1], v[70:71] op_sel_hi:[0,1]
	v_pk_mul_f32 v[12:13], v[0:1], v[62:63] op_sel_hi:[0,1]
	v_pk_mul_f32 v[16:17], v[0:1], v[60:61] op_sel_hi:[0,1]
	v_pk_mul_f32 v[56:57], v[0:1], v[56:57] op_sel_hi:[0,1]
	s_waitcnt vmcnt(0)
	v_pk_mul_f32 v[10:11], v[52:53], v[10:11]
	v_pk_mul_f32 v[12:13], v[54:55], v[12:13]
	v_pk_mul_f32 v[16:17], v[48:49], v[16:17]
	v_pk_mul_f32 v[48:49], v[50:51], v[56:57]
	v_cvt_pk_bf16_f32 v10, v10, v11
	v_cvt_pk_bf16_f32 v11, v12, v13
	v_cvt_pk_bf16_f32 v12, v16, v17
	v_cvt_pk_bf16_f32 v13, v48, v49
	global_store_dwordx4 v[46:47], v[10:13], off
	global_load_dwordx4 v[46:49], v[26:27], off offset:256
	s_nop 0
	global_load_dwordx4 v[50:53], v[26:27], off offset:272
	v_lshlrev_b32_e32 v10, 16, v6
	v_and_b32_e32 v11, 0xffff0000, v6
	v_lshlrev_b32_e32 v6, 16, v7
	v_and_b32_e32 v7, 0xffff0000, v7
	v_pk_mul_f32 v[16:17], v[10:11], v[10:11]
	v_pk_mul_f32 v[54:55], v[6:7], v[6:7]
	v_add_f32_e32 v0, v16, v17
	v_lshlrev_b32_e32 v12, 16, v8
	v_and_b32_e32 v13, 0xffff0000, v8
	v_add_f32_e32 v0, v54, v0
	v_pk_mul_f32 v[56:57], v[12:13], v[12:13]
	v_add_f32_e32 v0, v55, v0
	v_lshlrev_b32_e32 v8, 16, v9
	v_and_b32_e32 v9, 0xffff0000, v9
	v_add_f32_e32 v0, v56, v0
	v_pk_mul_f32 v[58:59], v[8:9], v[8:9]
	v_add_f32_e32 v0, v57, v0
	v_add_f32_e32 v0, v58, v0
	v_add_f32_e32 v0, v59, v0
	ds_bpermute_b32 v15, v64, v0
	v_mul_f32_e32 v16, 0x4b800000, v14
	v_cmp_gt_f32_e64 s[8:9], s16, v14
	s_waitcnt lgkmcnt(0)
	v_add_f32_e32 v0, v0, v15
	ds_bpermute_b32 v15, v65, v0
	v_cndmask_b32_e64 v14, v14, v16, s[8:9]
	v_rsq_f32_e32 v16, v14
	s_waitcnt lgkmcnt(0)
	v_add_f32_e32 v0, v0, v15
	ds_bpermute_b32 v15, v66, v0
	s_waitcnt lgkmcnt(0)
	v_add_f32_e32 v0, v0, v15
	ds_bpermute_b32 v14, v67, v0
	v_mul_f32_e32 v15, 0x45800000, v16
	v_cndmask_b32_e64 v16, v16, v15, s[8:9]
	v_pk_mul_f32 v[54:55], v[16:17], v[80:81] op_sel_hi:[0,1]
	v_pk_mul_f32 v[56:57], v[16:17], v[76:77] op_sel_hi:[0,1]
	v_pk_mul_f32 v[58:59], v[16:17], v[74:75] op_sel_hi:[0,1]
	v_pk_mul_f32 v[16:17], v[16:17], v[72:73] op_sel_hi:[0,1]
	s_waitcnt vmcnt(1)
	v_pk_mul_f32 v[46:47], v[46:47], v[54:55]
	v_pk_mul_f32 v[48:49], v[48:49], v[56:57]
	s_waitcnt vmcnt(0)
	v_pk_mul_f32 v[50:51], v[50:51], v[58:59]
	v_pk_mul_f32 v[16:17], v[52:53], v[16:17]
	v_cvt_pk_bf16_f32 v46, v46, v47
	v_cvt_pk_bf16_f32 v47, v48, v49
	v_cvt_pk_bf16_f32 v48, v50, v51
	v_cvt_pk_bf16_f32 v49, v16, v17
	global_store_dwordx4 v[44:45], v[46:49], off
	s_and_saveexec_b64 s[12:13], s[6:7]
	s_cbranch_execz .LBB0_1354
	global_load_dwordx4 v[44:47], v[24:25], off offset:256
	global_load_dwordx4 v[48:51], v[24:25], off offset:272
	s_waitcnt lgkmcnt(0)
	v_add_f32_e32 v0, v0, v14
	v_fmamk_f32 v0, v0, 0x3c000000, v198
	v_mul_f32_e32 v14, 0x4b800000, v0
	v_cmp_gt_f32_e64 s[8:9], s16, v0
	s_nop 1
	v_cndmask_b32_e64 v0, v0, v14, s[8:9]
	v_rsq_f32_e32 v0, v0
	s_nop 0
	v_mul_f32_e32 v14, 0x45800000, v0
	v_cndmask_b32_e64 v0, v0, v14, s[8:9]
	v_mul_f32_e32 v0, 0x3dd53b94, v0
	v_pk_mul_f32 v[10:11], v[0:1], v[10:11] op_sel_hi:[0,1]
	v_pk_mul_f32 v[6:7], v[0:1], v[6:7] op_sel_hi:[0,1]
	v_pk_mul_f32 v[12:13], v[0:1], v[12:13] op_sel_hi:[0,1]
	v_pk_mul_f32 v[8:9], v[0:1], v[8:9] op_sel_hi:[0,1]
	s_waitcnt vmcnt(1)
	v_pk_mul_f32 v[10:11], v[10:11], v[44:45]
	v_pk_mul_f32 v[14:15], v[6:7], v[46:47]
	s_waitcnt vmcnt(0)
	v_pk_mul_f32 v[12:13], v[12:13], v[48:49]
	v_pk_mul_f32 v[16:17], v[8:9], v[50:51]
	v_cvt_pk_bf16_f32 v6, v10, v11
	v_cvt_pk_bf16_f32 v7, v14, v15
	v_cvt_pk_bf16_f32 v8, v12, v13
	v_cvt_pk_bf16_f32 v9, v16, v17
	global_store_dwordx4 v[42:43], v[6:9], off

; __device__ __forceinline__ void unpack8(const u32x4 w, float* f) { f[0] = bflo(w.x); f[1] = bfhi(w.x); f[2] = bflo(w.y); f[3] = bfhi(w.y); f[4] = bflo(w.z); f[5] = bfhi(w.z); f[6] = bflo(w.w); f[7] = bfhi(w.w); }
; __device__ __forceinline__ u32x4 pack8f(const float* f) { u32x4 w; w.x = cvtpk(f[0], f[1]); w.y = cvtpk(f[2], f[3]); w.z = cvtpk(f[4], f[5]); w.w = cvtpk(f[6], f[7]); return w; }
; __device__ __forceinline__ void post_proj_row(ArgsP a, int l, int row, int lane) {
;     unsigned char* ws = a->ws;
;     bf16_t* P = (bf16_t*)(ws + WS_PROJ) + (size_t)row * NINP;
;     const u32x4 ld_d0 = *(const u32x4*)(P + 16 * lane), ld_d1 = *(const u32x4*)(P + 16 * lane + 8);
;     const u32x4 ld_f0 = *(const u32x4*)(P + C_FQ + 8 * lane), ld_f1 = *(const u32x4*)(P + C_FQ + 512 + 8 * lane), ld_f2 = *(const u32x4*)(P + C_FQ + 1024 + 8 * lane);
;     const u32x4 ld_q = *(const u32x4*)(P + C_MQ + 8 * lane);
;     const u32x2 ld_c = *(const u32x2*)(P + C_CKV + 4 * lane);
;     const u32x4 ld_k = *(const u32x4*)(P + C_KR + 8 * (lane & 7));
;     const unsigned short ld_ff = P[C_FF + (lane < 6 ? lane : 0)];
;     {
;         float x[16]; unpack8(ld_d0, x); unpack8(ld_d1, x + 8);
;         float ss = 0.f;
; #pragma unroll
;         for (int i = 0; i < 16; ++i) ss += x[i] * x[i];
;         ss += __shfl_xor(ss, 1); ss += __shfl_xor(ss, 2);
;         const float rstd = rsqrtf(ss * (1.0f / 64.0f) + RMS_EPS);
;         const float* g = (lane < 32 ? a->in[I_DQN] : a->in[I_DKN]) + l * 64 + (lane & 3) * 16;
;         const float rq = rstd;
; #pragma unroll
;         for (int i = 0; i < 16; ++i) x[i] = x[i] * rq * g[i];
;         if ((lane & 3) == 0) {
;             const float* cp = (const float*)(ws + WS_COSP) + row * 8; const float* sp = (const float*)(ws + WS_SINP) + row * 8;
; #pragma unroll
;             for (int i = 0; i < 8; ++i) { const float x1 = x[i], x2 = x[i + 8], c = cp[i], s = sp[i]; x[i] = x1 * c - x2 * s; x[i + 8] = x2 * c + x1 * s; }
;         }
;         *(u32x4*)(P + 16 * lane) = pack8f(x); *(u32x4*)(P + 16 * lane + 8) = pack8f(x + 8);
.LBB0_1416:
	v_lshl_add_u64 v[54:55], s[18:19], 0, v[22:23]
	s_mov_b64 s[12:13], 0x14000000
	v_add_co_u32_e32 v2, vcc, 0x14000000, v54
	v_lshl_add_u64 v[56:57], v[54:55], 0, s[12:13]
	s_nop 0
	v_addc_co_u32_e32 v3, vcc, 0, v55, vcc
	global_load_dwordx4 v[60:63], v[56:57], off offset:16
	global_load_dwordx4 v[64:67], v[2:3], off
	v_lshl_add_u64 v[58:59], s[18:19], 0, v[0:1]
	v_add_co_u32_e32 v6, vcc, s33, v58
	s_mov_b32 s2, 0x14001000
	s_nop 0
	v_addc_co_u32_e32 v7, vcc, 0, v59, vcc
	v_add_co_u32_e32 v8, vcc, s2, v58
	v_lshl_add_u64 v[50:51], s[18:19], 0, v[46:47]
	v_lshl_add_u64 v[48:49], s[18:19], 0, v[44:45]
	v_lshl_add_u64 v[2:3], s[18:19], 0, v[42:43]
	v_addc_co_u32_e32 v9, vcc, 0, v59, vcc
	global_load_dwordx4 v[68:71], v[32:33], off offset:48
	global_load_dwordx4 v[88:91], v[32:33], off offset:32
	global_load_dwordx4 v[92:95], v[32:33], off offset:16
	global_load_dwordx4 v[72:75], v[32:33], off
	global_load_ushort v86, v[2:3], off
	global_load_dwordx2 v[52:53], v[50:51], off
	s_waitcnt vmcnt(7)
	v_lshlrev_b32_e32 v76, 16, v60
	global_load_dwordx4 v[2:5], v[48:49], off
	global_load_dwordx4 v[18:21], v[6:7], off offset:3072
	s_waitcnt lgkmcnt(0)
	global_load_dwordx4 v[14:17], v[8:9], off
	global_load_dwordx4 v[10:13], v[8:9], off offset:1024
	s_nop 0
	global_load_dwordx4 v[6:9], v[8:9], off offset:3584
	s_waitcnt vmcnt(11)
	v_lshlrev_b32_e32 v98, 16, v64
	v_and_b32_e32 v99, 0xffff0000, v64
	v_lshlrev_b32_e32 v64, 16, v65
	v_and_b32_e32 v65, 0xffff0000, v65
	v_pk_mul_f32 v[106:107], v[98:99], v[98:99]
	v_pk_mul_f32 v[108:109], v[64:65], v[64:65]
	v_add_f32_e32 v106, v106, v107
	v_lshlrev_b32_e32 v104, 16, v66
	v_and_b32_e32 v105, 0xffff0000, v66
	v_add_f32_e32 v106, v108, v106
	v_pk_mul_f32 v[110:111], v[104:105], v[104:105]
	v_add_f32_e32 v106, v109, v106
	v_add_f32_e32 v106, v110, v106
	v_lshlrev_b32_e32 v87, 16, v67
	v_add_f32_e32 v106, v111, v106
	v_and_b32_e32 v77, 0xffff0000, v60
	v_and_b32_e32 v112, 0xffff0000, v67
	v_fmac_f32_e32 v106, v87, v87
	v_pk_mul_f32 v[100:101], v[76:77], v[76:77]
	v_fmac_f32_e32 v106, v112, v112
	v_lshlrev_b32_e32 v60, 16, v61
	v_and_b32_e32 v61, 0xffff0000, v61
	v_add_f32_e32 v100, v100, v106
	v_pk_mul_f32 v[102:103], v[60:61], v[60:61]
	v_add_f32_e32 v100, v101, v100
	v_lshlrev_b32_e32 v78, 16, v62
	v_and_b32_e32 v79, 0xffff0000, v62
	v_add_f32_e32 v100, v102, v100
	v_pk_mul_f32 v[66:67], v[78:79], v[78:79]
	v_add_f32_e32 v100, v103, v100
	v_and_b32_e32 v96, 0xffff0000, v63
	v_lshlrev_b32_e32 v97, 16, v63
	v_add_f32_e32 v66, v66, v100
	v_pk_mul_f32 v[62:63], v[96:97], v[96:97]
	v_add_f32_e32 v66, v67, v66
	v_add_f32_e32 v63, v63, v66
	v_add_f32_e32 v62, v62, v63
	ds_bpermute_b32 v63, v80, v62
	s_waitcnt lgkmcnt(0)
	v_add_f32_e32 v62, v62, v63
	ds_bpermute_b32 v63, v81, v62
	s_waitcnt lgkmcnt(0)
	v_add_f32_e32 v62, v62, v63
	v_fmamk_f32 v62, v62, 0x3c800000, v198
	v_mul_f32_e32 v63, 0x4b800000, v62
	v_cmp_gt_f32_e32 vcc, s16, v62
	s_nop 1
	v_cndmask_b32_e32 v62, v62, v63, vcc
	v_rsq_f32_e32 v62, v62
	s_nop 0
	v_mul_f32_e32 v63, 0x45800000, v62
	v_cndmask_b32_e32 v100, v62, v63, vcc
	v_mbcnt_lo_u32_b32 v120, -1, 0
	v_mov_b32_e32 v121, 0x3e38aa3b
	v_cmp_gt_u32_e32 vcc, 32, v120
	s_nop 1
	v_cndmask_b32_e32 v121, 1.0, v121, vcc
	v_mul_f32_e32 v100, v100, v121
	v_pk_mul_f32 v[62:63], v[100:101], v[98:99] op_sel_hi:[0,1]
	v_pk_mul_f32 v[64:65], v[100:101], v[64:65] op_sel_hi:[0,1]
	v_pk_mul_f32 v[66:67], v[100:101], v[104:105] op_sel_hi:[0,1]
	v_mul_f32_e32 v87, v100, v87
	v_pk_mul_f32 v[98:99], v[100:101], v[76:77] op_sel_hi:[0,1]
	v_pk_mul_f32 v[60:61], v[100:101], v[60:61] op_sel_hi:[0,1]
	v_pk_mul_f32 v[102:103], v[100:101], v[78:79] op_sel_hi:[0,1]
	v_mul_f32_e32 v101, v100, v97
	v_mov_b32_e32 v97, v112
	s_waitcnt vmcnt(7)
	v_pk_mul_f32 v[78:79], v[72:73], v[62:63]
	v_pk_mul_f32 v[76:77], v[74:75], v[64:65]
	v_mul_f32_e32 v72, v94, v87
	v_pk_mul_f32 v[64:65], v[90:91], v[60:61]
	v_pk_mul_f32 v[60:61], v[100:101], v[96:97] op_sel_hi:[0,1]
	v_mov_b32_e32 v94, v71
	v_pk_mul_f32 v[74:75], v[92:93], v[66:67]
	v_pk_mul_f32 v[62:63], v[88:89], v[98:99]
	v_pk_mul_f32 v[66:67], v[68:69], v[102:103]
	v_mul_f32_e32 v70, v70, v101
	v_pk_mul_f32 v[68:69], v[94:95], v[60:61]
	s_and_saveexec_b64 s[12:13], s[8:9]
	s_cbranch_execz .LBB0_1418
	s_ashr_i32 s27, s26, 31
	s_lshl_b64 s[42:43], s[26:27], 2
	s_add_u32 s44, s38, s42
	s_addc_u32 s45, s39, s43
	s_add_u32 s42, s40, s42
	s_addc_u32 s43, s41, s43
	global_load_dwordx4 v[88:91], v1, s[44:45] offset:16
	global_load_dwordx4 v[92:95], v1, s[44:45]
	global_load_dwordx4 v[96:99], v1, s[42:43] offset:16
	global_load_dwordx4 v[100:103], v1, s[42:43]
	v_mov_b32_e32 v71, v68
	v_mov_b32_e32 v73, v69
	s_waitcnt vmcnt(0)
	v_pk_mul_f32 v[60:61], v[62:63], v[100:101]
	s_nop 0
	v_pk_fma_f32 v[60:61], v[78:79], v[92:93], v[60:61] neg_lo:[0,0,1] neg_hi:[0,0,1]
	v_pk_mul_f32 v[78:79], v[78:79], v[100:101]
	s_nop 0
	v_pk_fma_f32 v[62:63], v[62:63], v[92:93], v[78:79]
	v_pk_mul_f32 v[78:79], v[64:65], v[102:103]
	s_nop 0
	v_pk_fma_f32 v[92:93], v[76:77], v[94:95], v[78:79] neg_lo:[0,0,1] neg_hi:[0,0,1]
	v_pk_mul_f32 v[76:77], v[76:77], v[102:103]
	v_mov_b32_e32 v78, v60
	v_pk_fma_f32 v[64:65], v[64:65], v[94:95], v[76:77]
	v_pk_mul_f32 v[76:77], v[66:67], v[96:97]
	v_mov_b32_e32 v79, v61
	v_pk_fma_f32 v[94:95], v[74:75], v[88:89], v[76:77] neg_lo:[0,0,1] neg_hi:[0,0,1]
	v_pk_mul_f32 v[74:75], v[74:75], v[96:97]
	v_mov_b32_e32 v76, v92
	v_pk_fma_f32 v[66:67], v[66:67], v[88:89], v[74:75]
	v_pk_mul_f32 v[74:75], v[70:71], v[98:99]
	v_mul_f32_e32 v70, v70, v90
	v_pk_fma_f32 v[88:89], v[72:73], v[90:91], v[74:75] neg_lo:[0,0,1] neg_hi:[0,0,1]
	v_mul_f32_e32 v72, v72, v98
	v_mov_b32_e32 v98, v91
	v_pk_mul_f32 v[68:69], v[68:69], v[98:99]
	v_mov_b32_e32 v77, v93
	v_mov_b32_e32 v71, v68
	v_mov_b32_e32 v73, v69
	v_pk_add_f32 v[70:71], v[70:71], v[72:73]
	v_mov_b32_e32 v74, v94
	v_mov_b32_e32 v75, v95
	v_mov_b32_e32 v72, v88
	v_mov_b32_e32 v69, v89
	v_mov_b32_e32 v68, v71
